# v42 + nt (instead of sc1) on all GEMM1 epilogue stores
# speedup vs baseline: 1.0196x; 1.0196x over previous
.LBB0_171:
	s_andn2_b64 vcc, exec, s[18:19]
	s_cbranch_vccnz .LBB0_173
	v_mul_f32_e32 v138, 0xbfb8aa3b, v110
	v_exp_f32_e32 v151, v138
	v_mul_f32_e32 v138, 0xbfb8aa3b, v111
	v_exp_f32_e32 v153, v138
	v_mul_f32_e32 v155, 0xbfb8aa3b, v113
	v_add_f32_e32 v151, 1.0, v151
	v_rcp_f32_e32 v154, v151
	v_add_f32_e32 v151, 1.0, v153
	v_mul_f32_e32 v153, 0xbfb8aa3b, v112
	v_exp_f32_e32 v153, v153
	v_exp_f32_e32 v157, v155
	v_rcp_f32_e32 v155, v151
	v_mul_f32_e32 v167, 0xbfb8aa3b, v109
	v_add_f32_e32 v151, 1.0, v153
	v_rcp_f32_e32 v156, v151
	v_add_f32_e32 v151, 1.0, v157
	v_rcp_f32_e32 v157, v151
	v_mul_f32_e32 v151, 0xbfb8aa3b, v106
	v_exp_f32_e32 v151, v151
	v_mul_f32_e32 v153, 0xbfb8aa3b, v107
	v_exp_f32_e32 v153, v153
	v_exp_f32_e32 v169, v167
	v_add_f32_e32 v151, 1.0, v151
	v_rcp_f32_e32 v166, v151
	v_add_f32_e32 v151, 1.0, v153
	v_mul_f32_e32 v153, 0xbfb8aa3b, v108
	v_exp_f32_e32 v153, v153
	v_rcp_f32_e32 v167, v151
	v_pk_mul_f32 v[156:157], v[112:113], v[156:157]
	v_lshl_add_u32 v138, s88, 7, v160
	v_add_f32_e32 v151, 1.0, v153
	v_rcp_f32_e32 v168, v151
	v_add_f32_e32 v151, 1.0, v169
	v_rcp_f32_e32 v169, v151
	v_pk_mul_f32 v[156:157], v[128:129], v[156:157]
	v_pk_mul_f32 v[166:167], v[106:107], v[166:167]
	v_pk_mul_f32 v[154:155], v[110:111], v[154:155]
	v_pk_mul_f32 v[168:169], v[108:109], v[168:169]
	v_mul_f32_e32 v151, 0xbfb8aa3b, v95
	v_pk_mul_f32 v[170:171], v[124:125], v[168:169]
	v_pk_mul_f32 v[168:169], v[122:123], v[166:167]
	v_cvt_pk_bf16_f32 v167, v156, v157
	v_lshlrev_b64 v[156:157], 1, v[138:139]
	v_mul_f32_e32 v138, 0xbfb8aa3b, v94
	v_exp_f32_e32 v138, v138
	v_pk_mul_f32 v[154:155], v[126:127], v[154:155]
	v_ashrrev_i32_e32 v153, 31, v152
	v_exp_f32_e32 v151, v151
	v_cvt_pk_bf16_f32 v166, v154, v155
	v_lshlrev_b64 v[154:155], 11, v[152:153]
	v_lshl_add_u64 v[154:155], s[10:11], 0, v[154:155]
	v_cvt_pk_bf16_f32 v168, v168, v169
	v_cvt_pk_bf16_f32 v169, v170, v171
	v_lshl_add_u64 v[154:155], v[154:155], 0, v[156:157]
	v_add_f32_e32 v138, 1.0, v138
	global_store_dwordx4 v[154:155], v[166:169], off nt
	v_mul_f32_e32 v153, 0xbfb8aa3b, v97
	v_exp_f32_e32 v153, v153
	v_rcp_f32_e32 v166, v138
	v_add_f32_e32 v138, 1.0, v151
	v_mul_f32_e32 v151, 0xbfb8aa3b, v96
	v_exp_f32_e32 v151, v151
	v_rcp_f32_e32 v167, v138
	v_or_b32_e32 v170, 16, v152
	v_ashrrev_i32_e32 v171, 31, v170
	v_add_f32_e32 v138, 1.0, v151
	v_rcp_f32_e32 v168, v138
	v_add_f32_e32 v138, 1.0, v153
	v_rcp_f32_e32 v169, v138
	v_mul_f32_e32 v138, 0xbfb8aa3b, v90
	v_exp_f32_e32 v138, v138
	v_mul_f32_e32 v151, 0xbfb8aa3b, v91
	v_exp_f32_e32 v151, v151
	v_mul_f32_e32 v153, 0xbfb8aa3b, v93
	v_add_f32_e32 v138, 1.0, v138
	v_rcp_f32_e32 v172, v138
	v_add_f32_e32 v138, 1.0, v151
	v_mul_f32_e32 v151, 0xbfb8aa3b, v92
	v_exp_f32_e32 v151, v151
	v_exp_f32_e32 v153, v153
	v_rcp_f32_e32 v173, v138
	v_pk_mul_f32 v[166:167], v[94:95], v[166:167]
	v_add_f32_e32 v138, 1.0, v151
	v_rcp_f32_e32 v174, v138
	v_add_f32_e32 v138, 1.0, v153
	v_rcp_f32_e32 v175, v138
	v_mul_f32_e32 v138, 0xbfb8aa3b, v78
	v_exp_f32_e32 v138, v138
	v_mul_f32_e32 v151, 0xbfb8aa3b, v79
	v_exp_f32_e32 v151, v151
	v_pk_mul_f32 v[168:169], v[96:97], v[168:169]
	v_pk_mul_f32 v[172:173], v[90:91], v[172:173]
	v_pk_mul_f32 v[174:175], v[92:93], v[174:175]
	v_lshlrev_b64 v[170:171], 11, v[170:171]
	v_pk_mul_f32 v[168:169], v[120:121], v[168:169]
	v_pk_mul_f32 v[166:167], v[118:119], v[166:167]
	v_pk_mul_f32 v[174:175], v[116:117], v[174:175]
	v_pk_mul_f32 v[172:173], v[114:115], v[172:173]
	v_lshl_add_u64 v[170:171], s[10:11], 0, v[170:171]
	v_cvt_pk_bf16_f32 v166, v166, v167
	v_cvt_pk_bf16_f32 v167, v168, v169
	v_cvt_pk_bf16_f32 v168, v172, v173
	v_cvt_pk_bf16_f32 v169, v174, v175
	v_lshl_add_u64 v[170:171], v[170:171], 0, v[156:157]
	v_add_f32_e32 v138, 1.0, v138
	global_store_dwordx4 v[170:171], v[166:169], off nt
	v_mul_f32_e32 v153, 0xbfb8aa3b, v81
	v_exp_f32_e32 v153, v153
	v_rcp_f32_e32 v166, v138
	v_add_f32_e32 v138, 1.0, v151
	v_mul_f32_e32 v151, 0xbfb8aa3b, v80
	v_exp_f32_e32 v151, v151
	v_rcp_f32_e32 v167, v138
	v_or_b32_e32 v170, 32, v152
	v_ashrrev_i32_e32 v171, 31, v170
	v_add_f32_e32 v138, 1.0, v151
	v_rcp_f32_e32 v168, v138
	v_add_f32_e32 v138, 1.0, v153
	v_rcp_f32_e32 v169, v138
	v_mul_f32_e32 v138, 0xbfb8aa3b, v74
	v_exp_f32_e32 v138, v138
	v_mul_f32_e32 v151, 0xbfb8aa3b, v75
	v_exp_f32_e32 v151, v151
	v_mul_f32_e32 v153, 0xbfb8aa3b, v77
	v_add_f32_e32 v138, 1.0, v138
	v_rcp_f32_e32 v172, v138
	v_add_f32_e32 v138, 1.0, v151
	v_mul_f32_e32 v151, 0xbfb8aa3b, v76
	v_exp_f32_e32 v151, v151
	v_exp_f32_e32 v153, v153
	v_rcp_f32_e32 v173, v138
	v_pk_mul_f32 v[166:167], v[78:79], v[166:167]
	v_add_f32_e32 v138, 1.0, v151
	v_rcp_f32_e32 v174, v138
	v_add_f32_e32 v138, 1.0, v153
	v_rcp_f32_e32 v175, v138
	v_mul_f32_e32 v138, 0xbfb8aa3b, v70
	v_exp_f32_e32 v138, v138
	v_mul_f32_e32 v151, 0xbfb8aa3b, v71
	v_exp_f32_e32 v151, v151
	v_pk_mul_f32 v[168:169], v[80:81], v[168:169]
	v_pk_mul_f32 v[172:173], v[74:75], v[172:173]
	v_pk_mul_f32 v[174:175], v[76:77], v[174:175]
	v_lshlrev_b64 v[170:171], 11, v[170:171]
	v_pk_mul_f32 v[168:169], v[104:105], v[168:169]
	v_pk_mul_f32 v[166:167], v[102:103], v[166:167]
	v_pk_mul_f32 v[174:175], v[100:101], v[174:175]
	v_pk_mul_f32 v[172:173], v[98:99], v[172:173]
	v_lshl_add_u64 v[170:171], s[10:11], 0, v[170:171]
	v_cvt_pk_bf16_f32 v166, v166, v167
	v_cvt_pk_bf16_f32 v167, v168, v169
	v_cvt_pk_bf16_f32 v168, v172, v173
	v_cvt_pk_bf16_f32 v169, v174, v175
	v_lshl_add_u64 v[170:171], v[170:171], 0, v[156:157]
	v_add_f32_e32 v138, 1.0, v138
	global_store_dwordx4 v[170:171], v[166:169], off nt
	v_mul_f32_e32 v153, 0xbfb8aa3b, v73
	v_exp_f32_e32 v153, v153
	v_rcp_f32_e32 v166, v138
	v_add_f32_e32 v138, 1.0, v151
	v_mul_f32_e32 v151, 0xbfb8aa3b, v72
	v_exp_f32_e32 v151, v151
	v_rcp_f32_e32 v167, v138
	v_or_b32_e32 v170, 48, v152
	v_ashrrev_i32_e32 v171, 31, v170
	v_add_f32_e32 v138, 1.0, v151
	v_rcp_f32_e32 v168, v138
	v_add_f32_e32 v138, 1.0, v153
	v_rcp_f32_e32 v169, v138
	v_mul_f32_e32 v138, 0xbfb8aa3b, v66
	v_exp_f32_e32 v138, v138
	v_mul_f32_e32 v151, 0xbfb8aa3b, v67
	v_exp_f32_e32 v151, v151
	v_mul_f32_e32 v153, 0xbfb8aa3b, v69
	v_add_f32_e32 v138, 1.0, v138
	v_rcp_f32_e32 v172, v138
	v_add_f32_e32 v138, 1.0, v151
	v_mul_f32_e32 v151, 0xbfb8aa3b, v68
	v_exp_f32_e32 v151, v151
	v_exp_f32_e32 v153, v153
	v_rcp_f32_e32 v173, v138
	v_pk_mul_f32 v[166:167], v[70:71], v[166:167]
	v_add_f32_e32 v138, 1.0, v151
	v_rcp_f32_e32 v174, v138
	v_add_f32_e32 v138, 1.0, v153
	v_rcp_f32_e32 v175, v138
	v_mul_f32_e32 v138, 0xbfb8aa3b, v46
	v_exp_f32_e32 v138, v138
	v_mul_f32_e32 v151, 0xbfb8aa3b, v47
	v_exp_f32_e32 v151, v151
	v_pk_mul_f32 v[168:169], v[72:73], v[168:169]
	v_pk_mul_f32 v[172:173], v[66:67], v[172:173]
	v_pk_mul_f32 v[174:175], v[68:69], v[174:175]
	v_lshlrev_b64 v[170:171], 11, v[170:171]
	v_pk_mul_f32 v[168:169], v[88:89], v[168:169]
	v_pk_mul_f32 v[166:167], v[86:87], v[166:167]
	v_pk_mul_f32 v[174:175], v[84:85], v[174:175]
	v_pk_mul_f32 v[172:173], v[82:83], v[172:173]
	v_lshl_add_u64 v[170:171], s[10:11], 0, v[170:171]
	v_cvt_pk_bf16_f32 v166, v166, v167
	v_cvt_pk_bf16_f32 v167, v168, v169
	v_cvt_pk_bf16_f32 v168, v172, v173
	v_cvt_pk_bf16_f32 v169, v174, v175
	v_lshl_add_u64 v[156:157], v[170:171], 0, v[156:157]
	v_add_f32_e32 v138, 1.0, v138
	global_store_dwordx4 v[156:157], v[166:169], off nt
	v_rcp_f32_e32 v156, v138
	v_add_f32_e32 v138, 1.0, v151
	v_mul_f32_e32 v151, 0xbfb8aa3b, v48
	v_exp_f32_e32 v151, v151
	v_mul_f32_e32 v153, 0xbfb8aa3b, v49
	v_exp_f32_e32 v153, v153
	v_rcp_f32_e32 v157, v138
	v_add_f32_e32 v138, 1.0, v151
	v_rcp_f32_e32 v166, v138
	v_add_f32_e32 v138, 1.0, v153
	v_rcp_f32_e32 v167, v138
	v_mul_f32_e32 v138, 0xbfb8aa3b, v42
	v_exp_f32_e32 v138, v138
	v_mul_f32_e32 v151, 0xbfb8aa3b, v43
	v_exp_f32_e32 v151, v151
	v_mul_f32_e32 v153, 0xbfb8aa3b, v45
	v_add_f32_e32 v138, 1.0, v138
	v_rcp_f32_e32 v168, v138
	v_add_f32_e32 v138, 1.0, v151
	v_mul_f32_e32 v151, 0xbfb8aa3b, v44
	v_exp_f32_e32 v151, v151
	v_exp_f32_e32 v153, v153
	v_rcp_f32_e32 v169, v138
	v_pk_mul_f32 v[156:157], v[46:47], v[156:157]
	v_add_f32_e32 v138, 1.0, v151
	v_rcp_f32_e32 v170, v138
	v_add_f32_e32 v138, 1.0, v153
	v_rcp_f32_e32 v171, v138
	v_mul_f32_e32 v138, 0xbfb8aa3b, v30
	v_exp_f32_e32 v138, v138
	v_mul_f32_e32 v151, 0xbfb8aa3b, v31
	v_pk_mul_f32 v[166:167], v[48:49], v[166:167]
	v_exp_f32_e32 v151, v151
	v_pk_mul_f32 v[172:173], v[64:65], v[166:167]
	v_pk_mul_f32 v[156:157], v[62:63], v[156:157]
	v_pk_mul_f32 v[166:167], v[42:43], v[168:169]
	v_pk_mul_f32 v[168:169], v[44:45], v[170:171]
	v_add_f32_e32 v138, 1.0, v138
	v_pk_mul_f32 v[170:171], v[60:61], v[168:169]
	v_pk_mul_f32 v[168:169], v[58:59], v[166:167]
	v_cvt_pk_bf16_f32 v166, v156, v157
	v_add_co_u32_e32 v156, vcc, s84, v154
	v_cvt_pk_bf16_f32 v167, v172, v173
	v_cvt_pk_bf16_f32 v168, v168, v169
	v_cvt_pk_bf16_f32 v169, v170, v171
	v_addc_co_u32_e32 v157, vcc, 0, v155, vcc
	global_store_dwordx4 v[156:157], v[166:169], off nt
	v_rcp_f32_e32 v156, v138
	v_add_f32_e32 v138, 1.0, v151
	v_mul_f32_e32 v151, 0xbfb8aa3b, v32
	v_exp_f32_e32 v151, v151
	v_mul_f32_e32 v153, 0xbfb8aa3b, v33
	v_exp_f32_e32 v153, v153
	v_rcp_f32_e32 v157, v138
	v_add_f32_e32 v138, 1.0, v151
	v_rcp_f32_e32 v166, v138
	v_add_f32_e32 v138, 1.0, v153
	v_rcp_f32_e32 v167, v138
	v_mul_f32_e32 v138, 0xbfb8aa3b, v26
	v_exp_f32_e32 v138, v138
	v_mul_f32_e32 v151, 0xbfb8aa3b, v27
	v_exp_f32_e32 v151, v151
	v_mul_f32_e32 v153, 0xbfb8aa3b, v29
	v_add_f32_e32 v138, 1.0, v138
	v_rcp_f32_e32 v168, v138
	v_add_f32_e32 v138, 1.0, v151
	v_mul_f32_e32 v151, 0xbfb8aa3b, v28
	v_exp_f32_e32 v151, v151
	v_exp_f32_e32 v153, v153
	v_rcp_f32_e32 v169, v138
	v_pk_mul_f32 v[156:157], v[30:31], v[156:157]
	v_add_f32_e32 v138, 1.0, v151
	v_rcp_f32_e32 v170, v138
	v_add_f32_e32 v138, 1.0, v153
	v_rcp_f32_e32 v171, v138
	v_mul_f32_e32 v138, 0xbfb8aa3b, v14
	v_exp_f32_e32 v138, v138
	v_mul_f32_e32 v151, 0xbfb8aa3b, v15
	v_pk_mul_f32 v[166:167], v[32:33], v[166:167]
	v_exp_f32_e32 v151, v151
	v_pk_mul_f32 v[172:173], v[56:57], v[166:167]
	v_pk_mul_f32 v[156:157], v[54:55], v[156:157]
	v_pk_mul_f32 v[166:167], v[26:27], v[168:169]
	v_pk_mul_f32 v[168:169], v[28:29], v[170:171]
	v_add_f32_e32 v138, 1.0, v138
	v_pk_mul_f32 v[170:171], v[52:53], v[168:169]
	v_pk_mul_f32 v[168:169], v[50:51], v[166:167]
	v_cvt_pk_bf16_f32 v166, v156, v157
	v_add_co_u32_e32 v156, vcc, s85, v154
	v_cvt_pk_bf16_f32 v167, v172, v173
	v_cvt_pk_bf16_f32 v168, v168, v169
	v_cvt_pk_bf16_f32 v169, v170, v171
	v_addc_co_u32_e32 v157, vcc, 0, v155, vcc
	global_store_dwordx4 v[156:157], v[166:169], off nt
	v_rcp_f32_e32 v156, v138
	v_add_f32_e32 v138, 1.0, v151
	v_mul_f32_e32 v151, 0xbfb8aa3b, v16
	v_exp_f32_e32 v151, v151
	v_mul_f32_e32 v153, 0xbfb8aa3b, v17
	v_exp_f32_e32 v153, v153
	v_rcp_f32_e32 v157, v138
	v_add_f32_e32 v138, 1.0, v151
	v_rcp_f32_e32 v166, v138
	v_add_f32_e32 v138, 1.0, v153
	v_rcp_f32_e32 v167, v138
	v_mul_f32_e32 v138, 0xbfb8aa3b, v10
	v_exp_f32_e32 v138, v138
	v_mul_f32_e32 v151, 0xbfb8aa3b, v11
	v_exp_f32_e32 v151, v151
	v_mul_f32_e32 v153, 0xbfb8aa3b, v13
	v_add_f32_e32 v138, 1.0, v138
	v_rcp_f32_e32 v168, v138
	v_add_f32_e32 v138, 1.0, v151
	v_mul_f32_e32 v151, 0xbfb8aa3b, v12
	v_exp_f32_e32 v151, v151
	v_exp_f32_e32 v153, v153
	v_rcp_f32_e32 v169, v138
	v_pk_mul_f32 v[156:157], v[14:15], v[156:157]
	v_add_f32_e32 v138, 1.0, v151
	v_rcp_f32_e32 v170, v138
	v_add_f32_e32 v138, 1.0, v153
	v_rcp_f32_e32 v171, v138
	v_mul_f32_e32 v138, 0xbfb8aa3b, v6
	v_exp_f32_e32 v138, v138
	v_mul_f32_e32 v151, 0xbfb8aa3b, v7
	v_pk_mul_f32 v[166:167], v[16:17], v[166:167]
	v_exp_f32_e32 v151, v151
	v_pk_mul_f32 v[172:173], v[40:41], v[166:167]
	v_pk_mul_f32 v[156:157], v[38:39], v[156:157]
	v_pk_mul_f32 v[166:167], v[10:11], v[168:169]
	v_pk_mul_f32 v[168:169], v[12:13], v[170:171]
	v_add_f32_e32 v138, 1.0, v138
	v_pk_mul_f32 v[170:171], v[36:37], v[168:169]
	v_pk_mul_f32 v[168:169], v[34:35], v[166:167]
	v_cvt_pk_bf16_f32 v166, v156, v157
	v_add_co_u32_e32 v156, vcc, s86, v154
	v_cvt_pk_bf16_f32 v167, v172, v173
	v_cvt_pk_bf16_f32 v168, v168, v169
	v_cvt_pk_bf16_f32 v169, v170, v171
	v_addc_co_u32_e32 v157, vcc, 0, v155, vcc
	global_store_dwordx4 v[156:157], v[166:169], off nt
	v_rcp_f32_e32 v156, v138
	v_add_f32_e32 v138, 1.0, v151
	v_mul_f32_e32 v151, 0xbfb8aa3b, v8
	v_exp_f32_e32 v151, v151
	v_mul_f32_e32 v153, 0xbfb8aa3b, v9
	v_exp_f32_e32 v153, v153
	v_rcp_f32_e32 v157, v138
	v_add_f32_e32 v138, 1.0, v151
	v_rcp_f32_e32 v166, v138
	v_add_f32_e32 v138, 1.0, v153
	v_rcp_f32_e32 v167, v138
	v_mul_f32_e32 v138, 0xbfb8aa3b, v2
	v_exp_f32_e32 v138, v138
	v_mul_f32_e32 v151, 0xbfb8aa3b, v3
	v_exp_f32_e32 v151, v151
	v_mul_f32_e32 v153, 0xbfb8aa3b, v5
	v_add_f32_e32 v138, 1.0, v138
	v_rcp_f32_e32 v168, v138
	v_add_f32_e32 v138, 1.0, v151
	v_mul_f32_e32 v151, 0xbfb8aa3b, v4
	v_exp_f32_e32 v151, v151
	v_exp_f32_e32 v153, v153
	v_rcp_f32_e32 v169, v138
	v_pk_mul_f32 v[166:167], v[8:9], v[166:167]
	v_add_f32_e32 v138, 1.0, v151
	v_rcp_f32_e32 v170, v138
	v_add_f32_e32 v138, 1.0, v153
	v_rcp_f32_e32 v171, v138
	v_pk_mul_f32 v[156:157], v[6:7], v[156:157]
	v_pk_mul_f32 v[172:173], v[24:25], v[166:167]
	v_pk_mul_f32 v[166:167], v[2:3], v[168:169]
	v_pk_mul_f32 v[168:169], v[4:5], v[170:171]
	v_pk_mul_f32 v[156:157], v[22:23], v[156:157]
	v_pk_mul_f32 v[170:171], v[20:21], v[168:169]
	v_pk_mul_f32 v[168:169], v[18:19], v[166:167]
	v_add_co_u32_e32 v154, vcc, 0x58000, v154
	v_cvt_pk_bf16_f32 v166, v156, v157
	v_cvt_pk_bf16_f32 v167, v172, v173
	v_cvt_pk_bf16_f32 v168, v168, v169
	v_cvt_pk_bf16_f32 v169, v170, v171
	v_addc_co_u32_e32 v155, vcc, 0, v155, vcc
	global_store_dwordx4 v[154:155], v[166:169], off nt

.LBB0_174:
	s_andn2_b64 vcc, exec, s[18:19]
	s_cbranch_vccnz .LBB0_176
	v_pk_mul_f32 v[156:157], v[128:129], v[112:113]
	v_pk_mul_f32 v[154:155], v[126:127], v[110:111]
	v_pk_mul_f32 v[166:167], v[124:125], v[108:109]
	v_ashrrev_i32_e32 v153, 31, v152
	v_lshl_add_u32 v138, s88, 7, v161
	v_pk_mul_f32 v[168:169], v[122:123], v[106:107]
	v_cvt_pk_bf16_f32 v154, v154, v155
	v_cvt_pk_bf16_f32 v155, v156, v157
	v_cvt_pk_bf16_f32 v157, v166, v167
	v_lshlrev_b64 v[166:167], 11, v[152:153]
	v_or_b32_e32 v170, 16, v152
	v_cvt_pk_bf16_f32 v156, v168, v169
	v_lshl_add_u64 v[166:167], s[34:35], 0, v[166:167]
	v_lshlrev_b64 v[168:169], 1, v[138:139]
	v_ashrrev_i32_e32 v171, 31, v170
	v_lshl_add_u64 v[166:167], v[166:167], 0, v[168:169]
	v_lshlrev_b64 v[170:171], 11, v[170:171]
	global_store_dwordx4 v[166:167], v[154:157], off nt
	v_pk_mul_f32 v[172:173], v[116:117], v[92:93]
	v_pk_mul_f32 v[174:175], v[114:115], v[90:91]
	v_pk_mul_f32 v[156:157], v[120:121], v[96:97]
	v_pk_mul_f32 v[154:155], v[118:119], v[94:95]
	v_lshl_add_u64 v[170:171], s[34:35], 0, v[170:171]
	v_cvt_pk_bf16_f32 v154, v154, v155
	v_cvt_pk_bf16_f32 v155, v156, v157
	v_cvt_pk_bf16_f32 v156, v174, v175
	v_cvt_pk_bf16_f32 v157, v172, v173
	v_lshl_add_u64 v[170:171], v[170:171], 0, v[168:169]
	global_store_dwordx4 v[170:171], v[154:157], off nt
	v_or_b32_e32 v170, 32, v152
	v_ashrrev_i32_e32 v171, 31, v170
	v_lshlrev_b64 v[170:171], 11, v[170:171]
	v_pk_mul_f32 v[156:157], v[104:105], v[80:81]
	v_pk_mul_f32 v[154:155], v[102:103], v[78:79]
	v_pk_mul_f32 v[172:173], v[100:101], v[76:77]
	v_pk_mul_f32 v[174:175], v[98:99], v[74:75]
	v_lshl_add_u64 v[170:171], s[34:35], 0, v[170:171]
	v_cvt_pk_bf16_f32 v154, v154, v155
	v_cvt_pk_bf16_f32 v155, v156, v157
	v_cvt_pk_bf16_f32 v156, v174, v175
	v_cvt_pk_bf16_f32 v157, v172, v173
	v_lshl_add_u64 v[170:171], v[170:171], 0, v[168:169]
	global_store_dwordx4 v[170:171], v[154:157], off nt
	v_or_b32_e32 v170, 48, v152
	v_ashrrev_i32_e32 v171, 31, v170
	v_lshlrev_b64 v[170:171], 11, v[170:171]
	v_pk_mul_f32 v[156:157], v[88:89], v[72:73]
	v_pk_mul_f32 v[154:155], v[86:87], v[70:71]
	v_pk_mul_f32 v[172:173], v[84:85], v[68:69]
	v_pk_mul_f32 v[174:175], v[82:83], v[66:67]
	v_lshl_add_u64 v[170:171], s[34:35], 0, v[170:171]
	v_cvt_pk_bf16_f32 v154, v154, v155
	v_cvt_pk_bf16_f32 v155, v156, v157
	v_cvt_pk_bf16_f32 v156, v174, v175
	v_cvt_pk_bf16_f32 v157, v172, v173
	v_lshl_add_u64 v[168:169], v[170:171], 0, v[168:169]
	global_store_dwordx4 v[168:169], v[154:157], off nt
	v_pk_mul_f32 v[168:169], v[60:61], v[44:45]
	v_pk_mul_f32 v[170:171], v[58:59], v[42:43]
	v_pk_mul_f32 v[156:157], v[64:65], v[48:49]
	v_pk_mul_f32 v[154:155], v[62:63], v[46:47]
	s_nop 0
	v_cvt_pk_bf16_f32 v154, v154, v155
	v_cvt_pk_bf16_f32 v155, v156, v157
	v_cvt_pk_bf16_f32 v157, v168, v169
	v_add_co_u32_e32 v168, vcc, s84, v166
	v_cvt_pk_bf16_f32 v156, v170, v171
	s_nop 0
	v_addc_co_u32_e32 v169, vcc, 0, v167, vcc
	global_store_dwordx4 v[168:169], v[154:157], off nt
	v_pk_mul_f32 v[168:169], v[52:53], v[28:29]
	v_pk_mul_f32 v[170:171], v[50:51], v[26:27]
	v_pk_mul_f32 v[156:157], v[56:57], v[32:33]
	v_pk_mul_f32 v[154:155], v[54:55], v[30:31]
	s_nop 0
	v_cvt_pk_bf16_f32 v154, v154, v155
	v_cvt_pk_bf16_f32 v155, v156, v157
	v_cvt_pk_bf16_f32 v157, v168, v169
	v_add_co_u32_e32 v168, vcc, s85, v166
	v_cvt_pk_bf16_f32 v156, v170, v171
	s_nop 0
	v_addc_co_u32_e32 v169, vcc, 0, v167, vcc
	global_store_dwordx4 v[168:169], v[154:157], off nt
	v_pk_mul_f32 v[168:169], v[36:37], v[12:13]
	v_pk_mul_f32 v[170:171], v[34:35], v[10:11]
	v_pk_mul_f32 v[156:157], v[40:41], v[16:17]
	v_pk_mul_f32 v[154:155], v[38:39], v[14:15]
	s_nop 0
	v_cvt_pk_bf16_f32 v154, v154, v155
	v_cvt_pk_bf16_f32 v155, v156, v157
	v_cvt_pk_bf16_f32 v157, v168, v169
	v_add_co_u32_e32 v168, vcc, s86, v166
	v_cvt_pk_bf16_f32 v156, v170, v171
	s_nop 0
	v_addc_co_u32_e32 v169, vcc, 0, v167, vcc
	global_store_dwordx4 v[168:169], v[154:157], off nt
	v_pk_mul_f32 v[168:169], v[20:21], v[4:5]
	v_pk_mul_f32 v[170:171], v[18:19], v[2:3]
	v_pk_mul_f32 v[156:157], v[24:25], v[8:9]
	v_pk_mul_f32 v[154:155], v[22:23], v[6:7]
	v_add_co_u32_e32 v166, vcc, 0x58000, v166
	v_cvt_pk_bf16_f32 v154, v154, v155
	v_cvt_pk_bf16_f32 v155, v156, v157
	v_cvt_pk_bf16_f32 v156, v170, v171
	v_cvt_pk_bf16_f32 v157, v168, v169
	v_addc_co_u32_e32 v167, vcc, 0, v167, vcc
	global_store_dwordx4 v[166:167], v[154:157], off nt

.LBB0_182:
	s_ashr_i32 s21, s17, 5
	v_lshl_or_b32 v153, s88, 13, v162
	v_cvt_pk_bf16_f32 v126, v126, v127
	v_cvt_pk_bf16_f32 v127, v128, v129
	v_cvt_pk_bf16_f32 v128, v122, v123
	v_add_u32_e32 v122, s21, v153
	v_cvt_pk_bf16_f32 v129, v124, v125
	v_mad_i64_i32 v[122:123], s[18:19], v122, s87, v[140:141]
	global_store_dwordx4 v[122:123], v[126:129], off nt
	v_cvt_pk_bf16_f32 v110, v110, v111
	v_cvt_pk_bf16_f32 v111, v112, v113
	v_or_b32_e32 v126, 0x1000, v153
	v_cvt_pk_bf16_f32 v112, v106, v107
	v_add_u32_e32 v106, s21, v126
	v_mad_i64_i32 v[124:125], s[18:19], v106, s87, v[140:141]
	v_cvt_pk_bf16_f32 v94, v94, v95
	v_cvt_pk_bf16_f32 v95, v96, v97
	v_cvt_pk_bf16_f32 v96, v90, v91
	v_cvt_pk_bf16_f32 v97, v92, v93
	s_or_b32 s21, s21, 1
	global_store_dwordx4 v[124:125], v[94:97], off offset:512 nt
	v_cvt_pk_bf16_f32 v90, v102, v103
	v_cvt_pk_bf16_f32 v91, v104, v105
	v_add_u32_e32 v94, s21, v153
	v_cvt_pk_bf16_f32 v92, v98, v99
	v_cvt_pk_bf16_f32 v93, v100, v101
	v_mad_i64_i32 v[94:95], s[18:19], v94, s87, v[140:141]
	global_store_dwordx4 v[94:95], v[90:93], off nt
	v_cvt_pk_bf16_f32 v78, v78, v79
	v_cvt_pk_bf16_f32 v79, v80, v81
	v_cvt_pk_bf16_f32 v80, v74, v75
	v_add_u32_e32 v74, s21, v126
	v_or_b32_e32 v90, 48, v152
	v_cvt_pk_bf16_f32 v81, v76, v77
	v_mad_i64_i32 v[74:75], s[18:19], v74, s87, v[140:141]
	v_ashrrev_i32_e32 v91, 5, v90
	global_store_dwordx4 v[74:75], v[78:81], off nt
	v_cvt_pk_bf16_f32 v70, v70, v71
	v_cvt_pk_bf16_f32 v71, v72, v73
	v_add_u32_e32 v80, v91, v153
	v_mov_b64_e32 v[78:79], s[28:29]
	v_cvt_pk_bf16_f32 v72, v66, v67
	v_add_u32_e32 v66, v91, v126
	v_mad_i64_i32 v[80:81], s[18:19], v80, s87, v[78:79]
	v_mad_i64_i32 v[66:67], s[18:19], v66, s87, v[78:79]
	v_cvt_pk_bf16_f32 v76, v82, v83
	v_lshlrev_b32_e32 v82, 5, v90
	s_add_i32 s18, s17, 0x80
	v_and_b32_e32 v138, 0x3e0, v82
	s_ashr_i32 s21, s18, 5
	v_lshl_add_u64 v[80:81], v[80:81], 0, v[138:139]
	v_mov_b32_e32 v151, v139
	v_lshl_add_u64 v[66:67], v[66:67], 0, v[138:139]
	v_cvt_pk_bf16_f32 v46, v46, v47
	v_cvt_pk_bf16_f32 v47, v48, v49
	v_cvt_pk_bf16_f32 v48, v42, v43
	v_add_u32_e32 v42, s21, v126
	v_cvt_pk_bf16_f32 v113, v108, v109
	v_cvt_pk_bf16_f32 v106, v118, v119
	v_cvt_pk_bf16_f32 v107, v120, v121
	v_cvt_pk_bf16_f32 v108, v114, v115
	v_cvt_pk_bf16_f32 v109, v116, v117
	v_cvt_pk_bf16_f32 v74, v86, v87
	v_cvt_pk_bf16_f32 v75, v88, v89
	v_cvt_pk_bf16_f32 v77, v84, v85
	v_lshl_add_u64 v[80:81], v[80:81], 0, v[150:151]
	v_cvt_pk_bf16_f32 v73, v68, v69
	v_lshl_add_u64 v[66:67], v[66:67], 0, v[150:151]
	v_cvt_pk_bf16_f32 v49, v44, v45
	v_mad_i64_i32 v[42:43], s[18:19], v42, s87, v[140:141]
	global_store_dwordx4 v[124:125], v[110:113], off nt
	global_store_dwordx4 v[122:123], v[106:109], off offset:512 nt
	global_store_dwordx4 v[80:81], v[74:77], off nt
	global_store_dwordx4 v[66:67], v[70:73], off nt
	global_store_dwordx4 v[42:43], v[46:49], off nt
	v_cvt_pk_bf16_f32 v30, v30, v31
	v_cvt_pk_bf16_f32 v31, v32, v33
	v_add_u32_e32 v48, 0x90, v152
	v_ashrrev_i32_e32 v49, 5, v48
	v_add_u32_e32 v46, v49, v153
	v_lshlrev_b32_e32 v48, 5, v48
	v_cvt_pk_bf16_f32 v32, v26, v27
	v_add_u32_e32 v26, v49, v126
	s_addk_i32 s17, 0xa0
	v_mad_i64_i32 v[46:47], s[18:19], v46, s87, v[78:79]
	v_and_b32_e32 v138, 0x3e0, v48
	v_mad_i64_i32 v[26:27], s[18:19], v26, s87, v[78:79]
	s_ashr_i32 s17, s17, 5
	v_cvt_pk_bf16_f32 v62, v62, v63
	v_cvt_pk_bf16_f32 v63, v64, v65
	v_cvt_pk_bf16_f32 v64, v58, v59
	v_add_u32_e32 v58, s21, v153
	v_lshl_add_u64 v[46:47], v[46:47], 0, v[138:139]
	v_lshl_add_u64 v[26:27], v[26:27], 0, v[138:139]
	v_cvt_pk_bf16_f32 v14, v14, v15
	v_cvt_pk_bf16_f32 v15, v16, v17
	v_cvt_pk_bf16_f32 v16, v10, v11
	v_add_u32_e32 v10, s17, v126
	v_cvt_pk_bf16_f32 v65, v60, v61
	v_mad_i64_i32 v[58:59], s[18:19], v58, s87, v[140:141]
	v_cvt_pk_bf16_f32 v42, v54, v55
	v_cvt_pk_bf16_f32 v43, v56, v57
	v_cvt_pk_bf16_f32 v44, v50, v51
	v_cvt_pk_bf16_f32 v45, v52, v53
	v_lshl_add_u64 v[46:47], v[46:47], 0, v[150:151]
	v_cvt_pk_bf16_f32 v33, v28, v29
	v_lshl_add_u64 v[26:27], v[26:27], 0, v[150:151]
	v_cvt_pk_bf16_f32 v17, v12, v13
	v_mad_i64_i32 v[10:11], s[18:19], v10, s87, v[140:141]
	global_store_dwordx4 v[58:59], v[62:65], off nt
	global_store_dwordx4 v[46:47], v[42:45], off nt
	global_store_dwordx4 v[26:27], v[30:33], off nt
	global_store_dwordx4 v[10:11], v[14:17], off nt
	v_cvt_pk_bf16_f32 v6, v6, v7
	v_cvt_pk_bf16_f32 v7, v8, v9
	v_add_u32_e32 v16, 0xb0, v152
	v_ashrrev_i32_e32 v17, 5, v16
	v_add_u32_e32 v14, v17, v153
	v_lshlrev_b32_e32 v16, 5, v16
	v_cvt_pk_bf16_f32 v8, v2, v3
	v_add_u32_e32 v2, v17, v126
	v_mad_i64_i32 v[14:15], s[18:19], v14, s87, v[78:79]
	v_and_b32_e32 v138, 0x3e0, v16
	v_mad_i64_i32 v[2:3], s[18:19], v2, s87, v[78:79]
	v_add_u32_e32 v30, s17, v153
	v_lshl_add_u64 v[14:15], v[14:15], 0, v[138:139]
	v_lshl_add_u64 v[2:3], v[2:3], 0, v[138:139]
	v_cvt_pk_bf16_f32 v26, v38, v39
	v_cvt_pk_bf16_f32 v27, v40, v41
	v_cvt_pk_bf16_f32 v28, v34, v35
	v_cvt_pk_bf16_f32 v29, v36, v37
	v_mad_i64_i32 v[30:31], s[18:19], v30, s87, v[140:141]
	v_cvt_pk_bf16_f32 v10, v22, v23
	v_cvt_pk_bf16_f32 v11, v24, v25
	v_cvt_pk_bf16_f32 v12, v18, v19
	v_cvt_pk_bf16_f32 v13, v20, v21
	v_lshl_add_u64 v[14:15], v[14:15], 0, v[150:151]
	v_cvt_pk_bf16_f32 v9, v4, v5
	v_lshl_add_u64 v[2:3], v[2:3], 0, v[150:151]
	global_store_dwordx4 v[30:31], v[26:29], off nt
	global_store_dwordx4 v[14:15], v[10:13], off nt
	global_store_dwordx4 v[2:3], v[6:9], off nt
	s_andn2_b64 vcc, exec, s[0:1]
	s_mov_b64 s[0:1], -1
	s_cbranch_vccnz .LBB0_159
